# v61 plus swa sink value fetched by a scalar load in the unit prologue instead of a vector load after the tile loop
# baseline (speedup 1.0000x reference)
.LBB0_244:
	s_or_b64 exec, exec, s[98:99]
	s_waitcnt vmcnt(0)
	s_waitcnt lgkmcnt(0)
	s_add_u32 s98, s72, s12
	s_addc_u32 s99, s73, s13
	s_ashr_i32 s71, s70, 31
	s_lshl_b64 s[100:101], s[70:71], 2
	s_add_u32 s98, s98, s100
	s_addc_u32 s99, s99, s101
	s_load_dword s101, s[98:99], 0x0

.LBB0_264:
	s_waitcnt lgkmcnt(0)
	s_add_u32 s5, s72, s12
	s_addc_u32 s14, s73, s13
	s_ashr_i32 s71, s70, 31
	s_lshl_b64 s[18:19], s[70:71], 2
	s_add_u32 s18, s5, s18
	s_addc_u32 s19, s14, s19
	v_mov_b32_e32 v4, s101
	v_and_b32_e32 v3, 64, v147
	v_xor_b32_e32 v2, 16, v147
	v_add_u32_e32 v3, 64, v3
	v_cmp_lt_i32_e32 vcc, v2, v3
	v_or_b32_e32 v50, s22, v144
	v_xor_b32_e32 v5, 32, v147
	v_cndmask_b32_e32 v6, v147, v2, vcc
	v_lshlrev_b32_e32 v6, 2, v6
	ds_bpermute_b32 v7, v6, v158
	v_ashrrev_i32_e32 v51, 31, v50
	ds_bpermute_b32 v6, v6, v159
	v_cmp_lt_i32_e32 vcc, v5, v3
	v_lshlrev_b64 v[2:3], 12, v[50:51]
	v_lshl_add_u64 v[2:3], s[8:9], 0, v[2:3]
	s_lshl_b64 s[20:21], s[20:21], 1
	v_lshlrev_b32_e32 v0, 1, v128
	v_cndmask_b32_e32 v5, v147, v5, vcc
	v_lshl_add_u64 v[2:3], v[2:3], 0, s[20:21]
	v_lshlrev_b32_e32 v5, 2, v5
	v_lshl_add_u64 v[52:53], v[2:3], 0, v[0:1]
	s_waitcnt lgkmcnt(0)
	v_add_f32_e32 v2, v158, v7
	v_add_f32_e32 v3, v159, v6
	ds_bpermute_b32 v6, v5, v2
	s_mov_b32 s5, 0x3fb8aa3b
	ds_bpermute_b32 v5, v5, v3
	v_add_u32_e32 v54, v225, v128
	s_waitcnt vmcnt(0) lgkmcnt(0)
	v_add_f32_e32 v2, v2, v6
	s_barrier
	v_add_f32_e32 v3, v3, v5
	v_add_u32_e32 v55, v225, v226
	v_fma_f32 v7, v4, s5, -v166
	v_fma_f32 v4, v4, s5, -v167
	v_exp_f32_e32 v7, v7
	v_exp_f32_e32 v4, v4
	v_add_f32_e32 v2, v7, v2
	v_add_f32_e32 v51, v4, v3
	v_div_scale_f32 v3, s[18:19], v2, v2, 1.0
	v_rcp_f32_e32 v6, v3
	v_div_scale_f32 v5, s[18:19], v51, v51, 1.0
	v_rcp_f32_e32 v7, v5
	v_fma_f32 v9, -v3, v6, 1.0
	v_div_scale_f32 v4, vcc, 1.0, v2, 1.0
	v_fmac_f32_e32 v6, v9, v6
	v_fma_f32 v10, -v5, v7, 1.0
	v_mul_f32_e32 v9, v4, v6
	v_div_scale_f32 v8, s[42:43], 1.0, v51, 1.0
	v_fmac_f32_e32 v7, v10, v7
	v_fma_f32 v11, -v3, v9, v4
	v_mul_f32_e32 v10, v8, v7
	v_fmac_f32_e32 v9, v11, v6
	v_fma_f32 v12, -v5, v10, v8
	v_fma_f32 v3, -v3, v9, v4
	v_fmac_f32_e32 v10, v12, v7
	v_div_fmas_f32 v3, v3, v6, v9
	v_fma_f32 v4, -v5, v10, v8
	v_div_fixup_f32 v14, v3, v2, 1.0
	s_mov_b64 vcc, s[42:43]
	v_div_fmas_f32 v56, v4, v7, v10
	v_pk_mul_f32 v[4:5], v[48:49], v[14:15] op_sel_hi:[1,0]
	v_pk_mul_f32 v[2:3], v[46:47], v[14:15] op_sel_hi:[1,0]
	v_pk_mul_f32 v[8:9], v[44:45], v[14:15] op_sel_hi:[1,0]
	v_pk_mul_f32 v[6:7], v[42:43], v[14:15] op_sel_hi:[1,0]
	v_pk_mul_f32 v[12:13], v[40:41], v[14:15] op_sel_hi:[1,0]
	v_pk_mul_f32 v[10:11], v[38:39], v[14:15] op_sel_hi:[1,0]
	v_pk_mul_f32 v[16:17], v[36:37], v[14:15] op_sel_hi:[1,0]
	v_pk_mul_f32 v[14:15], v[34:35], v[14:15] op_sel_hi:[1,0]
	ds_write_b128 v54, v[2:5] offset:32768
	ds_write_b128 v54, v[6:9] offset:32832
	ds_write_b128 v54, v[10:13] offset:32896
	ds_write_b128 v54, v[14:17] offset:32960
	s_waitcnt lgkmcnt(0)
	v_div_fixup_f32 v34, v56, v51, 1.0
	v_pk_mul_f32 v[4:5], v[32:33], v[34:35] op_sel_hi:[1,0]
	v_pk_mul_f32 v[2:3], v[30:31], v[34:35] op_sel_hi:[1,0]
	v_pk_mul_f32 v[8:9], v[28:29], v[34:35] op_sel_hi:[1,0]
	v_pk_mul_f32 v[6:7], v[26:27], v[34:35] op_sel_hi:[1,0]
	v_pk_mul_f32 v[12:13], v[24:25], v[34:35] op_sel_hi:[1,0]
	v_pk_mul_f32 v[10:11], v[22:23], v[34:35] op_sel_hi:[1,0]
	v_pk_mul_f32 v[16:17], v[20:21], v[34:35] op_sel_hi:[1,0]
	v_pk_mul_f32 v[14:15], v[18:19], v[34:35] op_sel_hi:[1,0]
	ds_read_b128 v[18:21], v55 offset:32768
	ds_read_b128 v[22:25], v55 offset:32784
	ds_read_b128 v[26:29], v55 offset:32800
	ds_read_b128 v[30:33], v55 offset:32816
	s_waitcnt lgkmcnt(0)
	ds_write_b128 v54, v[2:5] offset:32768
	ds_write_b128 v54, v[6:9] offset:32832
	ds_write_b128 v54, v[10:13] offset:32896
	ds_write_b128 v54, v[14:17] offset:32960
	s_waitcnt lgkmcnt(7)
	v_cvt_pk_bf16_f32 v2, v18, v19
	v_cvt_pk_bf16_f32 v3, v20, v21
	s_waitcnt lgkmcnt(6)
	v_cvt_pk_bf16_f32 v4, v22, v23
	v_cvt_pk_bf16_f32 v5, v24, v25
	s_waitcnt lgkmcnt(5)
	v_cvt_pk_bf16_f32 v6, v26, v27
	v_cvt_pk_bf16_f32 v7, v28, v29
	s_waitcnt lgkmcnt(4)
	v_cvt_pk_bf16_f32 v8, v30, v31
	v_cvt_pk_bf16_f32 v9, v32, v33
	global_store_dwordx4 v[52:53], v[2:5], off offset:2048
	global_store_dwordx4 v[52:53], v[6:9], off offset:2064
	s_waitcnt lgkmcnt(0)
	v_or_b32_e32 v18, 16, v50
	ds_read_b128 v[2:5], v55 offset:32768
	ds_read_b128 v[6:9], v55 offset:32784
	ds_read_b128 v[10:13], v55 offset:32800
	ds_read_b128 v[14:17], v55 offset:32816
	v_ashrrev_i32_e32 v19, 31, v18
	s_waitcnt lgkmcnt(0)
	v_lshlrev_b64 v[18:19], 12, v[18:19]
	v_lshl_add_u64 v[18:19], s[8:9], 0, v[18:19]
	v_lshl_add_u64 v[18:19], v[18:19], 0, s[20:21]
	v_lshl_add_u64 v[18:19], v[18:19], 0, v[0:1]
	s_waitcnt lgkmcnt(3)
	v_cvt_pk_bf16_f32 v2, v2, v3
	v_cvt_pk_bf16_f32 v3, v4, v5
	s_waitcnt lgkmcnt(2)
	v_cvt_pk_bf16_f32 v4, v6, v7
	v_cvt_pk_bf16_f32 v5, v8, v9
	s_mov_b64 s[20:21], 0
	s_waitcnt lgkmcnt(1)
	v_cvt_pk_bf16_f32 v6, v10, v11
	v_cvt_pk_bf16_f32 v7, v12, v13
	s_waitcnt lgkmcnt(0)
	v_cvt_pk_bf16_f32 v8, v14, v15
	v_cvt_pk_bf16_f32 v9, v16, v17
	global_store_dwordx4 v[18:19], v[2:5], off offset:2048
	global_store_dwordx4 v[18:19], v[6:9], off offset:2064
